# phase-7 q/k norm+rope batches: blocks 240-255 (which own a third V-transpose tile) hand trips 6-11 to waves 768-1535 as a 13th trip, on top of v31
# baseline (speedup 1.0000x reference)
; __device__ __forceinline__ void mlapost_rows(ArgP a, int l, int gw, int NGW, int lane) {
;     const bf16_t* Z = (const bf16_t*)(a->ws + OFF_Z); const bf16_t* QR = (const bf16_t*)(a->ws + OFF_QRAW); const bf16_t* KVR = (const bf16_t*)(a->ws + OFF_KVRAW);
;     const float* rope = (const float*)(a->ws + OFF_ROPE);
;     const float qscale = 0.10206207261596575f * LOG2E;
;     const int rw = lane >> 4, c = lane & 15; const bool act = c < 12, isrope = c >= 8 && c < 12;
;     const int cc = act ? c : 0;
;     const f32x4 gq0 = *(const f32x4*)(a->in[23] + l * 96 + 8 * cc), gq1 = *(const f32x4*)(a->in[23] + l * 96 + 8 * cc + 4);
;     const f32x4 gk0 = *(const f32x4*)(a->in[24] + l * 96 + 8 * cc), gk1 = *(const f32x4*)(a->in[24] + l * 96 + 8 * cc + 4);
;     const int axis = (c >> 1) & 1, hf = c & 1;
;     constexpr int NGRP = MTOT * 12 / 4;
;     for (int g0 = gw * 4; g0 < NGRP; g0 += NGW * 4) {
.LBB0_680:
	s_andn2_b64 vcc, exec, s[0:1]
	s_cbranch_vccnz .LBB0_764
	s_cmpk_gt_i32 s91, 0x62ff
	s_movk_i32 s19, 0x60
	v_mbcnt_lo_u32_b32 v1, -1, 0
	v_mbcnt_hi_u32_b32 v1, -1, v1
	s_cbranch_scc1 .LBB0_748
	s_add_u32 s0, s10, 0x11cd0000
	s_load_dwordx4 s[12:15], s[30:31], 0xb8
	s_addc_u32 s1, s11, 0
	s_add_u32 s2, s10, 0x100000
	s_mul_i32 s20, s62, 0x60
	s_addc_u32 s3, s11, 0
	v_and_b32_e32 v2, 15, v1
	s_ashr_i32 s21, s20, 31
	v_cmp_gt_u32_e64 s[38:39], 12, v2
	s_lshl_b64 s[20:21], s[20:21], 2
	s_waitcnt lgkmcnt(0)
	s_add_u32 s12, s12, s20
	v_cndmask_b32_e64 v20, 0, v2, s[38:39]
	s_addc_u32 s13, s13, s21
	v_lshlrev_b32_e32 v14, 5, v20
	global_load_dwordx4 v[2:5], v14, s[12:13] offset:16
	global_load_dwordx4 v[6:9], v14, s[12:13]
	s_add_u32 s12, s14, s20
	s_addc_u32 s13, s15, s21
	global_load_dwordx4 v[10:13], v14, s[12:13] offset:16
	s_nop 0
	global_load_dwordx4 v[14:17], v14, s[12:13]
	v_and_b32_e32 v18, 12, v1
	v_readlane_b32 s13, v254, 48
	v_cmp_eq_u32_e64 s[40:41], 8, v18
	v_lshlrev_b32_e32 v18, 4, v20
	v_mov_b32_e32 v19, v0
	s_lshl_b32 s12, s89, 7
	s_lshl_b32 s13, s13, 4
	v_ashrrev_i32_e32 v21, 4, v1
	v_and_b32_e32 v22, 1, v1
	v_lshl_add_u64 v[36:37], s[10:11], 0, v[18:19]
	v_and_b32_e32 v18, 2, v1
	s_add_i32 s13, s13, s12
	v_lshlrev_b32_e32 v34, 3, v20
	s_lshl_b32 s16, s91, 2
	v_cmp_lt_u32_e64 s[42:43], 7, v20
	v_cmp_eq_u32_e64 s[44:45], 0, v18
	v_cmp_eq_u32_e64 s[46:47], 0, v22
	s_lshl_b32 s20, s90, 5
	v_add_u32_e32 v35, s13, v21
	s_lshl_b32 s21, s90, 7
	s_mov_b32 s92, 0x18c00
	s_mov_b32 s93, -1
	s_cmpk_lg_i32 s90, 0x100
	s_cbranch_scc1 .Lmp_nomap
	s_cmpk_lt_i32 s91, 0x780
	s_cbranch_scc1 .Lmp_a
	s_mov_b32 s92, 0xc000
	s_branch .Lmp_nomap
.Lmp_a:
	s_cmpk_lt_i32 s91, 0x300
	s_cbranch_scc1 .Lmp_nomap
	s_cmpk_ge_i32 s91, 0x600
	s_cbranch_scc1 .Lmp_nomap
	s_sub_i32 s12, s91, 0x300
	s_and_b32 s13, s12, 0x7f
	s_lshr_b32 s12, s12, 7
	s_add_i32 s12, s12, 6
	s_lshl_b32 s12, s12, 11
	s_add_i32 s12, s12, s13
	s_addk_i32 s12, 0x780
	s_lshl_b32 s93, s12, 2

; __device__ __forceinline__ void mlapost_rows(ArgP a, int l, int gw, int NGW, int lane) {
;     ...
;     for (int g0 = gw * 4; g0 < NGRP; g0 += NGW * 4) {
;         u32x4 uin[4];
; #pragma unroll
;         for (int u = 0; u < 4; ++u) { const int item = (g0 + u) * 4 + rw; const size_t row = (size_t)(item / 12); const int hq = item % 12;
;             const bf16_t* src = hq < 6 ? QR + row * 576 + hq * 96 + 8 * cc : (cc < 8 ? KVR + row * 768 + (hq - 6) * 128 + 8 * cc : Z + row * INW + Z_KR + 8 * (cc - 8));
;             uin[u] = *(const u32x4*)src; }
.LBB0_683:
	s_or_b64 exec, exec, s[12:13]
	s_add_i32 s16, s16, s20
	s_cmp_lt_i32 s16, s92
	v_add_u32_e32 v35, s21, v35
	s_cbranch_scc1 .LBB0_684
	s_cmp_lt_i32 s93, 0
	s_cbranch_scc1 .LBB0_748
	s_mov_b32 s16, s93
	s_mov_b32 s92, 0
	s_mov_b32 s93, -1
	v_mbcnt_lo_u32_b32 v35, -1, 0
	v_mbcnt_hi_u32_b32 v35, -1, v35
	v_lshrrev_b32_e32 v35, 4, v35
	v_lshl_add_u32 v35, s16, 2, v35
